# v36
# speedup vs baseline: 1.0035x; 1.0001x over previous
; #define LAS __attribute__((address_space(3)))
; template <int MODE> __device__ __forceinline__ void transpose_item(const float* W, int K, int N, bf16_t* WT, LAS float* scr, int item, int lane) {
;     const int nblk = N / 32, kb = item / nblk, nb = item % nblk, k0 = 64 * kb, n0 = 32 * nb;
;     float tv[32];
; #pragma unroll
;     for (int i = 0; i < 32; ++i) tv[i] = W[(size_t)(k0 + 2 * i + (lane >> 5)) * N + n0 + (lane & 31)];
; template <int MODE> __device__ __forceinline__ void transpose_all(const float* W, int K, int N, bf16_t* WT, LAS float* scr, int gw, int NGW, int lane) {
;     asm volatile("" : "+v"(lane));
;     const int nitems = (K / 64) * (N / 32);
;     for (int it = gw; it < nitems; it += NGW) transpose_item<MODE>(W, K, N, WT, scr, it, lane);
.LBB0_42:
	s_ashr_i32 s6, s14, 31
	s_lshr_b32 s6, s6, 26
	s_add_i32 s7, s14, s6
	s_and_b32 s6, s7, 0xffffffc0
	s_lshl_b32 s7, s7, 5
	s_and_b32 s7, s7, 0xfffff800
	v_add_u32_e32 v16, s6, v5
	s_sub_i32 s10, s3, s7
	v_add_u32_e32 v18, 2, v16
	v_add_u32_e32 v20, 4, v16
	v_add_u32_e32 v22, 6, v16
	v_add_u32_e32 v24, 8, v16
	v_add_u32_e32 v26, 10, v16
	v_add_u32_e32 v28, 12, v16
	v_add_u32_e32 v30, 14, v16
	v_add_u32_e32 v40, 24, v16
	v_add_u32_e32 v42, 26, v16
	v_ashrrev_i32_e32 v17, 31, v16
	v_add_u32_e32 v32, 16, v16
	v_add_u32_e32 v34, 18, v16
	v_add_u32_e32 v36, 20, v16
	v_add_u32_e32 v38, 22, v16
	v_add_u32_e32 v44, 28, v16
	v_add_u32_e32 v46, 30, v16
	v_add_u32_e32 v48, 32, v16
	v_add_u32_e32 v50, 34, v16
	v_add_u32_e32 v52, 36, v16
	v_add_u32_e32 v54, 38, v16
	v_add_u32_e32 v56, 40, v16
	v_add_u32_e32 v58, 42, v16
	v_add_u32_e32 v60, 44, v16
	v_add_u32_e32 v62, 46, v16
	v_add_u32_e32 v64, 48, v16
	v_add_u32_e32 v66, 50, v16
	v_add_u32_e32 v68, 52, v16
	v_add_u32_e32 v70, 54, v16
	v_add_u32_e32 v72, 56, v16
	v_add_u32_e32 v74, 58, v16
	v_add_u32_e32 v76, 60, v16
	v_add_u32_e32 v78, 62, v16
	s_ashr_i32 s11, s10, 31
	v_ashrrev_i32_e32 v19, 31, v18
	v_ashrrev_i32_e32 v21, 31, v20
	v_ashrrev_i32_e32 v23, 31, v22
	v_ashrrev_i32_e32 v25, 31, v24
	v_ashrrev_i32_e32 v27, 31, v26
	v_ashrrev_i32_e32 v29, 31, v28
	v_ashrrev_i32_e32 v31, 31, v30
	v_ashrrev_i32_e32 v41, 31, v40
	v_ashrrev_i32_e32 v43, 31, v42
	v_lshlrev_b64 v[16:17], 13, v[16:17]
	v_ashrrev_i32_e32 v33, 31, v32
	v_ashrrev_i32_e32 v35, 31, v34
	v_ashrrev_i32_e32 v37, 31, v36
	v_ashrrev_i32_e32 v39, 31, v38
	v_ashrrev_i32_e32 v45, 31, v44
	v_ashrrev_i32_e32 v47, 31, v46
	v_ashrrev_i32_e32 v49, 31, v48
	v_ashrrev_i32_e32 v51, 31, v50
	v_ashrrev_i32_e32 v53, 31, v52
	v_ashrrev_i32_e32 v55, 31, v54
	v_ashrrev_i32_e32 v57, 31, v56
	v_ashrrev_i32_e32 v59, 31, v58
	v_ashrrev_i32_e32 v61, 31, v60
	v_ashrrev_i32_e32 v63, 31, v62
	v_ashrrev_i32_e32 v65, 31, v64
	v_ashrrev_i32_e32 v67, 31, v66
	v_ashrrev_i32_e32 v69, 31, v68
	v_ashrrev_i32_e32 v71, 31, v70
	v_ashrrev_i32_e32 v73, 31, v72
	v_ashrrev_i32_e32 v75, 31, v74
	v_ashrrev_i32_e32 v77, 31, v76
	v_ashrrev_i32_e32 v79, 31, v78
	v_lshlrev_b64 v[18:19], 13, v[18:19]
	v_lshlrev_b64 v[20:21], 13, v[20:21]
	v_lshlrev_b64 v[22:23], 13, v[22:23]
	v_lshlrev_b64 v[24:25], 13, v[24:25]
	v_lshlrev_b64 v[26:27], 13, v[26:27]
	v_lshlrev_b64 v[28:29], 13, v[28:29]
	v_lshlrev_b64 v[30:31], 13, v[30:31]
	v_lshlrev_b64 v[40:41], 13, v[40:41]
	v_lshlrev_b64 v[42:43], 13, v[42:43]
	v_lshl_add_u64 v[80:81], s[10:11], 2, v[0:1]
	v_lshlrev_b64 v[32:33], 13, v[32:33]
	v_lshlrev_b64 v[34:35], 13, v[34:35]
	v_lshlrev_b64 v[36:37], 13, v[36:37]
	v_lshlrev_b64 v[38:39], 13, v[38:39]
	v_lshlrev_b64 v[44:45], 13, v[44:45]
	v_lshlrev_b64 v[46:47], 13, v[46:47]
	v_lshlrev_b64 v[48:49], 13, v[48:49]
	v_lshlrev_b64 v[50:51], 13, v[50:51]
	v_lshlrev_b64 v[52:53], 13, v[52:53]
	v_lshlrev_b64 v[54:55], 13, v[54:55]
	v_lshlrev_b64 v[56:57], 13, v[56:57]
	v_lshlrev_b64 v[58:59], 13, v[58:59]
	v_lshlrev_b64 v[60:61], 13, v[60:61]
	v_lshlrev_b64 v[62:63], 13, v[62:63]
	v_lshlrev_b64 v[64:65], 13, v[64:65]
	v_lshlrev_b64 v[66:67], 13, v[66:67]
	v_lshlrev_b64 v[68:69], 13, v[68:69]
	v_lshlrev_b64 v[70:71], 13, v[70:71]
	v_lshlrev_b64 v[72:73], 13, v[72:73]
	v_lshlrev_b64 v[74:75], 13, v[74:75]
	v_lshlrev_b64 v[76:77], 13, v[76:77]
	v_lshlrev_b64 v[78:79], 13, v[78:79]
	v_lshl_add_u64 v[16:17], v[80:81], 0, v[16:17]
	v_lshl_add_u64 v[18:19], v[80:81], 0, v[18:19]
	v_lshl_add_u64 v[20:21], v[80:81], 0, v[20:21]
	v_lshl_add_u64 v[22:23], v[80:81], 0, v[22:23]
	v_lshl_add_u64 v[24:25], v[80:81], 0, v[24:25]
	v_lshl_add_u64 v[26:27], v[80:81], 0, v[26:27]
	v_lshl_add_u64 v[28:29], v[80:81], 0, v[28:29]
	v_lshl_add_u64 v[30:31], v[80:81], 0, v[30:31]
	v_lshl_add_u64 v[40:41], v[80:81], 0, v[40:41]
	v_lshl_add_u64 v[42:43], v[80:81], 0, v[42:43]
	v_lshl_add_u64 v[32:33], v[80:81], 0, v[32:33]
	v_lshl_add_u64 v[34:35], v[80:81], 0, v[34:35]
	v_lshl_add_u64 v[36:37], v[80:81], 0, v[36:37]
	v_lshl_add_u64 v[38:39], v[80:81], 0, v[38:39]
	v_lshl_add_u64 v[44:45], v[80:81], 0, v[44:45]
	v_lshl_add_u64 v[46:47], v[80:81], 0, v[46:47]
	v_lshl_add_u64 v[48:49], v[80:81], 0, v[48:49]
	v_lshl_add_u64 v[50:51], v[80:81], 0, v[50:51]
	v_lshl_add_u64 v[52:53], v[80:81], 0, v[52:53]
	v_lshl_add_u64 v[54:55], v[80:81], 0, v[54:55]
	v_lshl_add_u64 v[56:57], v[80:81], 0, v[56:57]
	v_lshl_add_u64 v[58:59], v[80:81], 0, v[58:59]
	v_lshl_add_u64 v[60:61], v[80:81], 0, v[60:61]
	v_lshl_add_u64 v[62:63], v[80:81], 0, v[62:63]
	v_lshl_add_u64 v[64:65], v[80:81], 0, v[64:65]
	v_lshl_add_u64 v[66:67], v[80:81], 0, v[66:67]
	v_lshl_add_u64 v[68:69], v[80:81], 0, v[68:69]
	v_lshl_add_u64 v[70:71], v[80:81], 0, v[70:71]
	v_lshl_add_u64 v[72:73], v[80:81], 0, v[72:73]
	v_lshl_add_u64 v[74:75], v[80:81], 0, v[74:75]
	v_lshl_add_u64 v[76:77], v[80:81], 0, v[76:77]
	v_lshl_add_u64 v[78:79], v[80:81], 0, v[78:79]
	global_load_dword v80, v[16:17], off nt
	global_load_dword v81, v[18:19], off nt
	global_load_dword v82, v[20:21], off nt
	global_load_dword v83, v[22:23], off nt
	global_load_dword v84, v[24:25], off nt
	global_load_dword v85, v[26:27], off nt
	global_load_dword v86, v[28:29], off nt
	global_load_dword v87, v[30:31], off nt
	global_load_dword v88, v[32:33], off nt
	global_load_dword v89, v[34:35], off nt
	global_load_dword v90, v[36:37], off nt
	global_load_dword v91, v[38:39], off nt
	global_load_dword v92, v[40:41], off nt
	global_load_dword v93, v[42:43], off nt
	global_load_dword v94, v[44:45], off nt
	global_load_dword v18, v[46:47], off nt
	global_load_dword v19, v[48:49], off nt
	global_load_dword v20, v[50:51], off nt
	global_load_dword v21, v[52:53], off nt
	global_load_dword v22, v[54:55], off nt
	global_load_dword v23, v[56:57], off nt
	global_load_dword v24, v[58:59], off nt
	global_load_dword v25, v[60:61], off nt
	global_load_dword v26, v[62:63], off nt
	global_load_dword v27, v[64:65], off nt
	global_load_dword v28, v[66:67], off nt
	global_load_dword v29, v[68:69], off nt
	global_load_dword v30, v[70:71], off nt
	global_load_dword v31, v[72:73], off nt
	global_load_dword v40, v[74:75], off nt
	global_load_dword v41, v[76:77], off nt
	global_load_dword v42, v[78:79], off nt
	s_waitcnt vmcnt(30)
; __device__ __forceinline__ unsigned cvt_pk_bf16(float lo, float hi) { const f32x2c v = {lo, hi}; const bf16x2c b = __builtin_convertvector(v, bf16x2c); return __builtin_bit_cast(unsigned, b); }
; #define LAS __attribute__((address_space(3)))
; template <int MODE> __device__ __forceinline__ void transpose_item(const float* W, int K, int N, bf16_t* WT, LAS float* scr, int item, int lane) {
;     ...
;     for (int i = 0; i < 32; ++i) scr[(2 * i + (lane >> 5)) * 33 + (lane & 31)] = tv[i];
;     asm volatile("s_waitcnt lgkmcnt(0)" ::: "memory");
;     const int c = lane & 7, dr0 = dest_row<MODE>(n0);
; #pragma unroll
;     for (int j = 0; j < 4; ++j) { const int n = (lane >> 3) + 8 * j; const LAS float* s = scr + (8 * c) * 33 + n;
;         u32x4 o; o.x = cvt_pk_bf16(s[0 * 33], s[1 * 33]); o.y = cvt_pk_bf16(s[2 * 33], s[3 * 33]); o.z = cvt_pk_bf16(s[4 * 33], s[5 * 33]); o.w = cvt_pk_bf16(s[6 * 33], s[7 * 33]);
;         *(u32x4*)(WT + (size_t)(dr0 + n) * K + k0 + 8 * c) = o; }
;     asm volatile("s_waitcnt lgkmcnt(0)" ::: "memory");
; template <int MODE> __device__ __forceinline__ void transpose_all(const float* W, int K, int N, bf16_t* WT, LAS float* scr, int gw, int NGW, int lane) {
;     ...
;     for (int it = gw; it < nitems; it += NGW) transpose_item<MODE>(W, K, N, WT, scr, it, lane);
	ds_write2_b32 v8, v80, v81 offset1:66
	s_waitcnt vmcnt(28)
	ds_write2_b32 v8, v82, v83 offset0:132 offset1:198
	s_waitcnt vmcnt(26)
	ds_write2_b32 v9, v84, v85 offset0:8 offset1:74
	s_waitcnt vmcnt(24)
	ds_write2_b32 v9, v86, v87 offset0:140 offset1:206
	s_waitcnt vmcnt(22)
	ds_write2_b32 v10, v88, v89 offset0:16 offset1:82
	s_waitcnt vmcnt(20)
	ds_write2_b32 v10, v90, v91 offset0:148 offset1:214
	s_waitcnt vmcnt(18)
	ds_write2_b32 v11, v92, v93 offset0:24 offset1:90
	s_waitcnt vmcnt(16)
	ds_write2_b32 v11, v94, v18 offset0:156 offset1:222
	s_waitcnt vmcnt(14)
	ds_write2_b32 v12, v19, v20 offset0:32 offset1:98
	s_waitcnt vmcnt(12)
	ds_write2_b32 v12, v21, v22 offset0:164 offset1:230
	s_waitcnt vmcnt(10)
	ds_write2_b32 v13, v23, v24 offset0:40 offset1:106
	s_waitcnt vmcnt(8)
	ds_write2_b32 v13, v25, v26 offset0:172 offset1:238
	s_waitcnt vmcnt(6)
	ds_write2_b32 v14, v27, v28 offset0:48 offset1:114
	s_waitcnt vmcnt(4)
	ds_write2_b32 v14, v29, v30 offset0:180 offset1:246
	s_waitcnt vmcnt(2)
	ds_write2_b32 v15, v31, v40 offset0:56 offset1:122
	s_waitcnt vmcnt(0)
	ds_write2_b32 v15, v41, v42 offset0:188 offset1:254
	s_waitcnt lgkmcnt(0)
	ds_read2_b32 v[20:21], v7 offset0:33 offset1:41
	ds_read2_b32 v[22:23], v7 offset1:8
	ds_read2_b32 v[24:25], v7 offset0:66 offset1:74
	ds_read2_b32 v[26:27], v7 offset0:99 offset1:107
	ds_read2_b32 v[28:29], v7 offset0:132 offset1:140
	ds_read2_b32 v[30:31], v7 offset0:165 offset1:173
	ds_read2_b32 v[40:41], v7 offset0:198 offset1:206
	ds_read2_b32 v[42:43], v7 offset0:231 offset1:239
	ds_read2_b32 v[44:45], v7 offset0:49 offset1:57
	ds_read2_b32 v[46:47], v7 offset0:16 offset1:24
	ds_read2_b32 v[48:49], v7 offset0:82 offset1:90
	ds_read2_b32 v[50:51], v7 offset0:115 offset1:123
	ds_read2_b32 v[52:53], v7 offset0:148 offset1:156
	ds_read2_b32 v[54:55], v7 offset0:181 offset1:189
	ds_read2_b32 v[56:57], v7 offset0:214 offset1:222
	ds_read2_b32 v[58:59], v7 offset0:247 offset1:255
	s_ashr_i32 s7, s6, 31
	v_add_u32_e32 v34, s10, v6
	v_lshl_add_u64 v[16:17], s[6:7], 1, v[2:3]
	v_add_u32_e32 v35, 8, v34
	v_add_u32_e32 v36, 16, v34
	v_add_u32_e32 v38, 24, v34
	v_mad_i64_i32 v[32:33], s[6:7], v34, s13, v[16:17]
	v_mad_i64_i32 v[34:35], s[6:7], v35, s13, v[16:17]
	v_mad_i64_i32 v[36:37], s[6:7], v36, s13, v[16:17]
	v_mad_i64_i32 v[38:39], s[6:7], v38, s13, v[16:17]
	s_waitcnt lgkmcnt(14)
	v_cvt_pk_bf16_f32 v16, v22, v20
	s_waitcnt lgkmcnt(12)
	v_cvt_pk_bf16_f32 v17, v24, v26
	s_waitcnt lgkmcnt(10)
	v_cvt_pk_bf16_f32 v18, v28, v30
	s_waitcnt lgkmcnt(8)
	v_cvt_pk_bf16_f32 v19, v40, v42
	v_cvt_pk_bf16_f32 v20, v23, v21
	v_cvt_pk_bf16_f32 v21, v25, v27
	v_cvt_pk_bf16_f32 v22, v29, v31
	v_cvt_pk_bf16_f32 v23, v41, v43
	s_waitcnt lgkmcnt(6)
	v_cvt_pk_bf16_f32 v24, v46, v44
	s_waitcnt lgkmcnt(4)
	v_cvt_pk_bf16_f32 v25, v48, v50
	s_waitcnt lgkmcnt(2)
	v_cvt_pk_bf16_f32 v26, v52, v54
	s_waitcnt lgkmcnt(0)
	v_cvt_pk_bf16_f32 v27, v56, v58
	v_cvt_pk_bf16_f32 v28, v47, v45
	v_cvt_pk_bf16_f32 v29, v49, v51
	v_cvt_pk_bf16_f32 v30, v53, v55
	v_cvt_pk_bf16_f32 v31, v57, v59
	global_store_dwordx4 v[32:33], v[16:19], off nt
	global_store_dwordx4 v[34:35], v[20:23], off nt
	global_store_dwordx4 v[36:37], v[24:27], off nt
	global_store_dwordx4 v[38:39], v[28:31], off nt
	s_waitcnt lgkmcnt(0)
	s_add_i32 s14, s14, s93
	s_add_i32 s3, s3, s12
	s_cmpk_lt_i32 s14, 0x1600
	s_cbranch_scc1 .LBB0_42

; #define LAS __attribute__((address_space(3)))
; template <int MODE> __device__ __forceinline__ int dest_row(int n0) {
;     if (MODE == 1) { return n0 < DFF ? (n0 / 128) * 256 + (n0 % 128) : ((n0 - DFF) / 128) * 256 + 128 + ((n0 - DFF) % 128); }
;     if (MODE == 2) { if (n0 >= 4096 && n0 < 6144) { const int t = n0 & ~255, s = n0 & 255; return t + 128 * ((s >> 5) & 1) + 32 * (s >> 6); } return n0; }
;     return n0;
; }
; template <int MODE> __device__ __forceinline__ void transpose_item(const float* W, int K, int N, bf16_t* WT, LAS float* scr, int item, int lane) {
;     const int nblk = N / 32, kb = item / nblk, nb = item % nblk, k0 = 64 * kb, n0 = 32 * nb;
;     float tv[32];
; #pragma unroll
;     for (int i = 0; i < 32; ++i) tv[i] = W[(size_t)(k0 + 2 * i + (lane >> 5)) * N + n0 + (lane & 31)];
.LBB0_45:
	s_mul_hi_i32 s8, s14, 0x2e8ba2e9
	s_lshr_b32 s9, s8, 31
	s_ashr_i32 s8, s8, 6
	s_add_i32 s9, s8, s9
	s_mul_i32 s10, s9, 0xffffd400
	s_lshl_b32 s8, s9, 6
	s_add_i32 s10, s3, s10
	v_add_u32_e32 v18, s8, v5
	s_ashr_i32 s11, s10, 31
	v_add_u32_e32 v26, 8, v18
	v_add_u32_e32 v28, 10, v18
	v_add_u32_e32 v30, 12, v18
	v_add_u32_e32 v40, 22, v18
	v_add_u32_e32 v42, 24, v18
	v_add_u32_e32 v44, 26, v18
	v_add_u32_e32 v46, 28, v18
	v_add_u32_e32 v48, 30, v18
	v_lshl_add_u64 v[16:17], s[10:11], 2, v[0:1]
	v_add_u32_e32 v20, 2, v18
	v_add_u32_e32 v22, 4, v18
	v_add_u32_e32 v24, 6, v18
	v_add_u32_e32 v32, 14, v18
	v_add_u32_e32 v34, 16, v18
	v_add_u32_e32 v36, 18, v18
	v_add_u32_e32 v38, 20, v18
	v_add_u32_e32 v50, 32, v18
	v_add_u32_e32 v52, 34, v18
	v_add_u32_e32 v54, 36, v18
	v_add_u32_e32 v56, 38, v18
	v_add_u32_e32 v58, 40, v18
	v_add_u32_e32 v60, 42, v18
	v_add_u32_e32 v62, 44, v18
	v_add_u32_e32 v64, 46, v18
	v_add_u32_e32 v66, 48, v18
	v_add_u32_e32 v68, 50, v18
	v_add_u32_e32 v70, 52, v18
	v_add_u32_e32 v72, 54, v18
	v_add_u32_e32 v74, 56, v18
	v_add_u32_e32 v76, 58, v18
	v_add_u32_e32 v78, 60, v18
	v_add_u32_e32 v80, 62, v18
	v_mad_i64_i32 v[18:19], s[22:23], v18, s13, v[16:17]
	v_mad_i64_i32 v[26:27], s[22:23], v26, s13, v[16:17]
	v_mad_i64_i32 v[28:29], s[22:23], v28, s13, v[16:17]
	v_mad_i64_i32 v[30:31], s[22:23], v30, s13, v[16:17]
	v_mad_i64_i32 v[40:41], s[22:23], v40, s13, v[16:17]
	v_mad_i64_i32 v[42:43], s[22:23], v42, s13, v[16:17]
	v_mad_i64_i32 v[44:45], s[22:23], v44, s13, v[16:17]
	v_mad_i64_i32 v[46:47], s[22:23], v46, s13, v[16:17]
	v_mad_i64_i32 v[48:49], s[22:23], v48, s13, v[16:17]
	v_mad_i64_i32 v[20:21], s[22:23], v20, s13, v[16:17]
	v_mad_i64_i32 v[22:23], s[22:23], v22, s13, v[16:17]
	v_mad_i64_i32 v[24:25], s[22:23], v24, s13, v[16:17]
	v_mad_i64_i32 v[32:33], s[22:23], v32, s13, v[16:17]
	v_mad_i64_i32 v[34:35], s[22:23], v34, s13, v[16:17]
	v_mad_i64_i32 v[36:37], s[22:23], v36, s13, v[16:17]
	v_mad_i64_i32 v[38:39], s[22:23], v38, s13, v[16:17]
	v_mad_i64_i32 v[50:51], s[22:23], v50, s13, v[16:17]
	v_mad_i64_i32 v[52:53], s[22:23], v52, s13, v[16:17]
	v_mad_i64_i32 v[54:55], s[22:23], v54, s13, v[16:17]
	v_mad_i64_i32 v[56:57], s[22:23], v56, s13, v[16:17]
	v_mad_i64_i32 v[58:59], s[22:23], v58, s13, v[16:17]
	v_mad_i64_i32 v[60:61], s[22:23], v60, s13, v[16:17]
	v_mad_i64_i32 v[62:63], s[22:23], v62, s13, v[16:17]
	v_mad_i64_i32 v[64:65], s[22:23], v64, s13, v[16:17]
	v_mad_i64_i32 v[66:67], s[22:23], v66, s13, v[16:17]
	v_mad_i64_i32 v[68:69], s[22:23], v68, s13, v[16:17]
	v_mad_i64_i32 v[70:71], s[22:23], v70, s13, v[16:17]
	v_mad_i64_i32 v[72:73], s[22:23], v72, s13, v[16:17]
	v_mad_i64_i32 v[74:75], s[22:23], v74, s13, v[16:17]
	v_mad_i64_i32 v[76:77], s[22:23], v76, s13, v[16:17]
	v_mad_i64_i32 v[78:79], s[22:23], v78, s13, v[16:17]
	v_mad_i64_i32 v[16:17], s[22:23], v80, s13, v[16:17]
	global_load_dword v80, v[18:19], off nt
	global_load_dword v81, v[20:21], off nt
	global_load_dword v82, v[22:23], off nt
	global_load_dword v83, v[24:25], off nt
	global_load_dword v84, v[26:27], off nt
	global_load_dword v85, v[28:29], off nt
	global_load_dword v86, v[30:31], off nt
	global_load_dword v87, v[32:33], off nt
	global_load_dword v88, v[34:35], off nt
	global_load_dword v89, v[36:37], off nt
	global_load_dword v90, v[38:39], off nt
	global_load_dword v91, v[40:41], off nt
	global_load_dword v92, v[42:43], off nt
	global_load_dword v93, v[44:45], off nt
	global_load_dword v94, v[46:47], off nt
	global_load_dword v26, v[48:49], off nt
	global_load_dword v27, v[50:51], off nt
	global_load_dword v28, v[52:53], off nt
	global_load_dword v29, v[54:55], off nt
	global_load_dword v30, v[56:57], off nt
	global_load_dword v31, v[58:59], off nt
	global_load_dword v40, v[60:61], off nt
	global_load_dword v41, v[62:63], off nt
	global_load_dword v42, v[64:65], off nt
	global_load_dword v43, v[66:67], off nt
	global_load_dword v44, v[68:69], off nt
	global_load_dword v45, v[70:71], off nt
	global_load_dword v46, v[72:73], off nt
	global_load_dword v47, v[74:75], off nt
	global_load_dword v95, v[76:77], off nt
	global_load_dword v48, v[78:79], off nt
	global_load_dword v49, v[16:17], off nt
	s_and_b32 s11, s7, 0x80
	s_mulk_i32 s9, 0xfea0
	s_and_b32 s15, s10, 0x1700
	s_lshr_b32 s22, s10, 1
	s_add_i32 s9, s14, s9
	s_or_b32 s11, s11, s15
	s_and_b32 s15, s22, 0x60
	s_and_b32 s9, s9, 0x7ffffc0
	s_or_b32 s11, s11, s15
	s_cmpk_eq_i32 s9, 0x80
	s_cselect_b32 s10, s11, s10
	v_add_u32_e32 v18, s10, v6
	s_ashr_i32 s9, s8, 31
	v_ashrrev_i32_e32 v19, 31, v18
	v_add_u32_e32 v20, 8, v18
	v_add_u32_e32 v22, 16, v18
	v_add_u32_e32 v24, 24, v18
	v_lshl_add_u64 v[16:17], s[8:9], 1, v[2:3]
	v_lshlrev_b64 v[18:19], 12, v[18:19]
	v_ashrrev_i32_e32 v21, 31, v20
	v_ashrrev_i32_e32 v23, 31, v22
	v_ashrrev_i32_e32 v25, 31, v24
	s_waitcnt vmcnt(30)
; __device__ __forceinline__ unsigned cvt_pk_bf16(float lo, float hi) { const f32x2c v = {lo, hi}; const bf16x2c b = __builtin_convertvector(v, bf16x2c); return __builtin_bit_cast(unsigned, b); }
; #define LAS __attribute__((address_space(3)))
; template <int MODE> __device__ __forceinline__ void transpose_item(const float* W, int K, int N, bf16_t* WT, LAS float* scr, int item, int lane) {
;     ...
;     for (int i = 0; i < 32; ++i) scr[(2 * i + (lane >> 5)) * 33 + (lane & 31)] = tv[i];
;     asm volatile("s_waitcnt lgkmcnt(0)" ::: "memory");
;     const int c = lane & 7, dr0 = dest_row<MODE>(n0);
; #pragma unroll
;     for (int j = 0; j < 4; ++j) { const int n = (lane >> 3) + 8 * j; const LAS float* s = scr + (8 * c) * 33 + n;
;         u32x4 o; o.x = cvt_pk_bf16(s[0 * 33], s[1 * 33]); o.y = cvt_pk_bf16(s[2 * 33], s[3 * 33]); o.z = cvt_pk_bf16(s[4 * 33], s[5 * 33]); o.w = cvt_pk_bf16(s[6 * 33], s[7 * 33]);
;         *(u32x4*)(WT + (size_t)(dr0 + n) * K + k0 + 8 * c) = o; }
;     asm volatile("s_waitcnt lgkmcnt(0)" ::: "memory");
	ds_write2_b32 v8, v80, v81 offset1:66
	s_waitcnt vmcnt(28)
	ds_write2_b32 v8, v82, v83 offset0:132 offset1:198
	s_waitcnt vmcnt(26)
	ds_write2_b32 v9, v84, v85 offset0:8 offset1:74
	s_waitcnt vmcnt(24)
	ds_write2_b32 v9, v86, v87 offset0:140 offset1:206
	s_waitcnt vmcnt(22)
	ds_write2_b32 v10, v88, v89 offset0:16 offset1:82
	s_waitcnt vmcnt(20)
	ds_write2_b32 v10, v90, v91 offset0:148 offset1:214
	s_waitcnt vmcnt(18)
	ds_write2_b32 v11, v92, v93 offset0:24 offset1:90
	s_waitcnt vmcnt(16)
	ds_write2_b32 v11, v94, v26 offset0:156 offset1:222
	s_waitcnt vmcnt(14)
	ds_write2_b32 v12, v27, v28 offset0:32 offset1:98
	s_waitcnt vmcnt(12)
	ds_write2_b32 v12, v29, v30 offset0:164 offset1:230
	s_waitcnt vmcnt(10)
	ds_write2_b32 v13, v31, v40 offset0:40 offset1:106
	s_waitcnt vmcnt(8)
	ds_write2_b32 v13, v41, v42 offset0:172 offset1:238
	s_waitcnt vmcnt(6)
	ds_write2_b32 v14, v43, v44 offset0:48 offset1:114
	s_waitcnt vmcnt(4)
	ds_write2_b32 v14, v45, v46 offset0:180 offset1:246
	s_waitcnt vmcnt(2)
	ds_write2_b32 v15, v47, v95 offset0:56 offset1:122
	s_waitcnt vmcnt(0)
	ds_write2_b32 v15, v48, v49 offset0:188 offset1:254
	v_lshl_add_u64 v[32:33], v[16:17], 0, v[18:19]
	v_lshlrev_b64 v[18:19], 12, v[20:21]
	v_lshlrev_b64 v[20:21], 12, v[22:23]
	v_lshlrev_b64 v[22:23], 12, v[24:25]
	s_waitcnt lgkmcnt(0)
	v_lshl_add_u64 v[36:37], v[16:17], 0, v[20:21]
	v_lshl_add_u64 v[38:39], v[16:17], 0, v[22:23]
	ds_read2_b32 v[20:21], v7 offset0:33 offset1:41
	ds_read2_b32 v[22:23], v7 offset1:8
	ds_read2_b32 v[24:25], v7 offset0:66 offset1:74
	ds_read2_b32 v[26:27], v7 offset0:99 offset1:107
	ds_read2_b32 v[28:29], v7 offset0:132 offset1:140
	ds_read2_b32 v[30:31], v7 offset0:165 offset1:173
	ds_read2_b32 v[40:41], v7 offset0:198 offset1:206
	ds_read2_b32 v[42:43], v7 offset0:231 offset1:239
	ds_read2_b32 v[44:45], v7 offset0:49 offset1:57
	ds_read2_b32 v[46:47], v7 offset0:16 offset1:24
	ds_read2_b32 v[48:49], v7 offset0:82 offset1:90
	ds_read2_b32 v[50:51], v7 offset0:115 offset1:123
	ds_read2_b32 v[52:53], v7 offset0:148 offset1:156
	ds_read2_b32 v[54:55], v7 offset0:181 offset1:189
	ds_read2_b32 v[56:57], v7 offset0:214 offset1:222
	ds_read2_b32 v[58:59], v7 offset0:247 offset1:255
	v_lshl_add_u64 v[34:35], v[16:17], 0, v[18:19]
	s_waitcnt lgkmcnt(14)
	v_cvt_pk_bf16_f32 v16, v22, v20
	s_waitcnt lgkmcnt(12)
	v_cvt_pk_bf16_f32 v17, v24, v26
	s_waitcnt lgkmcnt(10)
	v_cvt_pk_bf16_f32 v18, v28, v30
	s_waitcnt lgkmcnt(8)
	v_cvt_pk_bf16_f32 v19, v40, v42
	v_cvt_pk_bf16_f32 v20, v23, v21
	v_cvt_pk_bf16_f32 v21, v25, v27
	v_cvt_pk_bf16_f32 v22, v29, v31
	v_cvt_pk_bf16_f32 v23, v41, v43
	s_waitcnt lgkmcnt(6)
	v_cvt_pk_bf16_f32 v24, v46, v44
	s_waitcnt lgkmcnt(4)
	v_cvt_pk_bf16_f32 v25, v48, v50
	s_waitcnt lgkmcnt(2)
	v_cvt_pk_bf16_f32 v26, v52, v54
	s_waitcnt lgkmcnt(0)
	v_cvt_pk_bf16_f32 v27, v56, v58
	v_cvt_pk_bf16_f32 v28, v47, v45
	v_cvt_pk_bf16_f32 v29, v49, v51
	v_cvt_pk_bf16_f32 v30, v53, v55
	v_cvt_pk_bf16_f32 v31, v57, v59
	global_store_dwordx4 v[32:33], v[16:19], off nt
	global_store_dwordx4 v[34:35], v[20:23], off nt
	global_store_dwordx4 v[36:37], v[24:27], off nt
	global_store_dwordx4 v[38:39], v[28:31], off nt
	s_waitcnt lgkmcnt(0)
	s_add_i32 s14, s14, s93
	s_add_i32 s3, s3, s6
	s_add_i32 s7, s7, s12
	s_cmpk_lt_i32 s14, 0x2c00
	s_cbranch_scc1 .LBB0_45

; template <int MODE> __device__ __forceinline__ void transpose_item(const float* W, int K, int N, bf16_t* WT, LAS float* scr, int item, int lane) {
;     const int nblk = N / 32, kb = item / nblk, nb = item % nblk, k0 = 64 * kb, n0 = 32 * nb;
;     float tv[32];
; #pragma unroll
;     for (int i = 0; i < 32; ++i) tv[i] = W[(size_t)(k0 + 2 * i + (lane >> 5)) * N + n0 + (lane & 31)];
.LBB0_48:
	s_ashr_i32 s10, s7, 31
	s_lshr_b32 s10, s10, 26
	s_add_i32 s11, s7, s10
	s_and_b32 s10, s11, 0xffffffc0
	s_lshl_b32 s11, s11, 5
	s_and_b32 s11, s11, 0xfffff800
	v_add_u32_e32 v16, s10, v5
	s_sub_i32 s12, s3, s11
	v_add_u32_e32 v26, 10, v16
	v_add_u32_e32 v28, 12, v16
	v_add_u32_e32 v30, 14, v16
	v_add_u32_e32 v40, 24, v16
	v_add_u32_e32 v42, 26, v16
	v_add_u32_e32 v44, 28, v16
	v_add_u32_e32 v46, 30, v16
	v_ashrrev_i32_e32 v17, 31, v16
	v_add_u32_e32 v18, 2, v16
	v_add_u32_e32 v20, 4, v16
	v_add_u32_e32 v22, 6, v16
	v_add_u32_e32 v24, 8, v16
	v_add_u32_e32 v32, 16, v16
	v_add_u32_e32 v34, 18, v16
	v_add_u32_e32 v36, 20, v16
	v_add_u32_e32 v38, 22, v16
	v_add_u32_e32 v48, 32, v16
	v_add_u32_e32 v50, 34, v16
	v_add_u32_e32 v52, 36, v16
	v_add_u32_e32 v54, 38, v16
	v_add_u32_e32 v56, 40, v16
	v_add_u32_e32 v58, 42, v16
	v_add_u32_e32 v60, 44, v16
	v_add_u32_e32 v62, 46, v16
	v_add_u32_e32 v64, 48, v16
	v_add_u32_e32 v66, 50, v16
	v_add_u32_e32 v68, 52, v16
	v_add_u32_e32 v70, 54, v16
	v_add_u32_e32 v72, 56, v16
	v_add_u32_e32 v74, 58, v16
	v_add_u32_e32 v76, 60, v16
	v_add_u32_e32 v78, 62, v16
	s_ashr_i32 s13, s12, 31
	v_ashrrev_i32_e32 v27, 31, v26
	v_ashrrev_i32_e32 v29, 31, v28
	v_ashrrev_i32_e32 v31, 31, v30
	v_ashrrev_i32_e32 v41, 31, v40
	v_ashrrev_i32_e32 v43, 31, v42
	v_ashrrev_i32_e32 v45, 31, v44
	v_ashrrev_i32_e32 v47, 31, v46
	v_lshlrev_b64 v[16:17], 13, v[16:17]
	v_ashrrev_i32_e32 v19, 31, v18
	v_ashrrev_i32_e32 v21, 31, v20
	v_ashrrev_i32_e32 v23, 31, v22
	v_ashrrev_i32_e32 v25, 31, v24
	v_ashrrev_i32_e32 v33, 31, v32
	v_ashrrev_i32_e32 v35, 31, v34
	v_ashrrev_i32_e32 v37, 31, v36
	v_ashrrev_i32_e32 v39, 31, v38
	v_ashrrev_i32_e32 v49, 31, v48
	v_ashrrev_i32_e32 v51, 31, v50
	v_ashrrev_i32_e32 v53, 31, v52
	v_ashrrev_i32_e32 v55, 31, v54
	v_ashrrev_i32_e32 v57, 31, v56
	v_ashrrev_i32_e32 v59, 31, v58
	v_ashrrev_i32_e32 v61, 31, v60
	v_ashrrev_i32_e32 v63, 31, v62
	v_ashrrev_i32_e32 v65, 31, v64
	v_ashrrev_i32_e32 v67, 31, v66
	v_ashrrev_i32_e32 v69, 31, v68
	v_ashrrev_i32_e32 v71, 31, v70
	v_ashrrev_i32_e32 v73, 31, v72
	v_ashrrev_i32_e32 v75, 31, v74
	v_ashrrev_i32_e32 v77, 31, v76
	v_ashrrev_i32_e32 v79, 31, v78
	v_lshl_add_u64 v[80:81], s[12:13], 2, v[0:1]
	v_lshlrev_b64 v[26:27], 13, v[26:27]
	v_lshlrev_b64 v[28:29], 13, v[28:29]
	v_lshlrev_b64 v[30:31], 13, v[30:31]
	v_lshlrev_b64 v[40:41], 13, v[40:41]
	v_lshlrev_b64 v[42:43], 13, v[42:43]
	v_lshlrev_b64 v[44:45], 13, v[44:45]
	v_lshlrev_b64 v[46:47], 13, v[46:47]
	v_lshlrev_b64 v[18:19], 13, v[18:19]
	v_lshlrev_b64 v[20:21], 13, v[20:21]
	v_lshlrev_b64 v[22:23], 13, v[22:23]
	v_lshlrev_b64 v[24:25], 13, v[24:25]
	v_lshlrev_b64 v[32:33], 13, v[32:33]
	v_lshlrev_b64 v[34:35], 13, v[34:35]
	v_lshlrev_b64 v[36:37], 13, v[36:37]
	v_lshlrev_b64 v[38:39], 13, v[38:39]
	v_lshlrev_b64 v[48:49], 13, v[48:49]
	v_lshlrev_b64 v[50:51], 13, v[50:51]
	v_lshlrev_b64 v[52:53], 13, v[52:53]
	v_lshlrev_b64 v[54:55], 13, v[54:55]
	v_lshlrev_b64 v[56:57], 13, v[56:57]
	v_lshlrev_b64 v[58:59], 13, v[58:59]
	v_lshlrev_b64 v[60:61], 13, v[60:61]
	v_lshlrev_b64 v[62:63], 13, v[62:63]
	v_lshlrev_b64 v[64:65], 13, v[64:65]
	v_lshlrev_b64 v[66:67], 13, v[66:67]
	v_lshlrev_b64 v[68:69], 13, v[68:69]
	v_lshlrev_b64 v[70:71], 13, v[70:71]
	v_lshlrev_b64 v[72:73], 13, v[72:73]
	v_lshlrev_b64 v[74:75], 13, v[74:75]
	v_lshlrev_b64 v[76:77], 13, v[76:77]
	v_lshlrev_b64 v[78:79], 13, v[78:79]
	v_lshl_add_u64 v[16:17], v[80:81], 0, v[16:17]
	v_lshl_add_u64 v[26:27], v[80:81], 0, v[26:27]
	v_lshl_add_u64 v[28:29], v[80:81], 0, v[28:29]
	v_lshl_add_u64 v[30:31], v[80:81], 0, v[30:31]
	v_lshl_add_u64 v[40:41], v[80:81], 0, v[40:41]
	v_lshl_add_u64 v[42:43], v[80:81], 0, v[42:43]
	v_lshl_add_u64 v[44:45], v[80:81], 0, v[44:45]
	v_lshl_add_u64 v[46:47], v[80:81], 0, v[46:47]
	v_lshl_add_u64 v[18:19], v[80:81], 0, v[18:19]
	v_lshl_add_u64 v[20:21], v[80:81], 0, v[20:21]
	v_lshl_add_u64 v[22:23], v[80:81], 0, v[22:23]
	v_lshl_add_u64 v[24:25], v[80:81], 0, v[24:25]
	v_lshl_add_u64 v[32:33], v[80:81], 0, v[32:33]
	v_lshl_add_u64 v[34:35], v[80:81], 0, v[34:35]
	v_lshl_add_u64 v[36:37], v[80:81], 0, v[36:37]
	v_lshl_add_u64 v[38:39], v[80:81], 0, v[38:39]
	v_lshl_add_u64 v[48:49], v[80:81], 0, v[48:49]
	v_lshl_add_u64 v[50:51], v[80:81], 0, v[50:51]
	v_lshl_add_u64 v[52:53], v[80:81], 0, v[52:53]
	v_lshl_add_u64 v[54:55], v[80:81], 0, v[54:55]
	v_lshl_add_u64 v[56:57], v[80:81], 0, v[56:57]
	v_lshl_add_u64 v[58:59], v[80:81], 0, v[58:59]
	v_lshl_add_u64 v[60:61], v[80:81], 0, v[60:61]
	v_lshl_add_u64 v[62:63], v[80:81], 0, v[62:63]
	v_lshl_add_u64 v[64:65], v[80:81], 0, v[64:65]
	v_lshl_add_u64 v[66:67], v[80:81], 0, v[66:67]
	v_lshl_add_u64 v[68:69], v[80:81], 0, v[68:69]
	v_lshl_add_u64 v[70:71], v[80:81], 0, v[70:71]
	v_lshl_add_u64 v[72:73], v[80:81], 0, v[72:73]
	v_lshl_add_u64 v[74:75], v[80:81], 0, v[74:75]
	v_lshl_add_u64 v[76:77], v[80:81], 0, v[76:77]
	v_lshl_add_u64 v[78:79], v[80:81], 0, v[78:79]
	global_load_dword v80, v[16:17], off nt
	global_load_dword v81, v[18:19], off nt
	global_load_dword v82, v[20:21], off nt
	global_load_dword v83, v[22:23], off nt
	global_load_dword v84, v[24:25], off nt
	global_load_dword v85, v[26:27], off nt
	global_load_dword v86, v[28:29], off nt
	global_load_dword v87, v[30:31], off nt
	global_load_dword v88, v[32:33], off nt
	global_load_dword v89, v[34:35], off nt
	global_load_dword v90, v[36:37], off nt
	global_load_dword v91, v[38:39], off nt
	global_load_dword v92, v[40:41], off nt
	global_load_dword v93, v[42:43], off nt
	global_load_dword v94, v[44:45], off nt
	global_load_dword v26, v[46:47], off nt
	global_load_dword v27, v[48:49], off nt
	global_load_dword v28, v[50:51], off nt
	global_load_dword v29, v[52:53], off nt
	global_load_dword v30, v[54:55], off nt
	global_load_dword v31, v[56:57], off nt
	global_load_dword v40, v[58:59], off nt
	global_load_dword v41, v[60:61], off nt
	global_load_dword v42, v[62:63], off nt
	global_load_dword v43, v[64:65], off nt
	global_load_dword v44, v[66:67], off nt
	global_load_dword v45, v[68:69], off nt
	global_load_dword v95, v[70:71], off nt
	global_load_dword v96, v[72:73], off nt
	global_load_dword v97, v[74:75], off nt
	global_load_dword v46, v[76:77], off nt
	global_load_dword v47, v[78:79], off nt
	v_add_u32_e32 v18, s12, v6
	s_ashr_i32 s11, s10, 31
	v_ashrrev_i32_e32 v19, 31, v18
	v_add_u32_e32 v20, 8, v18
	v_add_u32_e32 v22, 16, v18
	v_add_u32_e32 v24, 24, v18
	v_lshl_add_u64 v[16:17], s[10:11], 1, v[2:3]
	v_lshlrev_b64 v[18:19], 11, v[18:19]
	v_ashrrev_i32_e32 v21, 31, v20
	v_ashrrev_i32_e32 v23, 31, v22
	v_ashrrev_i32_e32 v25, 31, v24
	s_waitcnt vmcnt(30)
; __device__ __forceinline__ unsigned cvt_pk_bf16(float lo, float hi) { const f32x2c v = {lo, hi}; const bf16x2c b = __builtin_convertvector(v, bf16x2c); return __builtin_bit_cast(unsigned, b); }
; #define LAS __attribute__((address_space(3)))
; template <int MODE> __device__ __forceinline__ void transpose_item(const float* W, int K, int N, bf16_t* WT, LAS float* scr, int item, int lane) {
;     ...
;     for (int i = 0; i < 32; ++i) scr[(2 * i + (lane >> 5)) * 33 + (lane & 31)] = tv[i];
;     asm volatile("s_waitcnt lgkmcnt(0)" ::: "memory");
;     const int c = lane & 7, dr0 = dest_row<MODE>(n0);
; #pragma unroll
;     for (int j = 0; j < 4; ++j) { const int n = (lane >> 3) + 8 * j; const LAS float* s = scr + (8 * c) * 33 + n;
;         u32x4 o; o.x = cvt_pk_bf16(s[0 * 33], s[1 * 33]); o.y = cvt_pk_bf16(s[2 * 33], s[3 * 33]); o.z = cvt_pk_bf16(s[4 * 33], s[5 * 33]); o.w = cvt_pk_bf16(s[6 * 33], s[7 * 33]);
;         *(u32x4*)(WT + (size_t)(dr0 + n) * K + k0 + 8 * c) = o; }
;     asm volatile("s_waitcnt lgkmcnt(0)" ::: "memory");
	ds_write2_b32 v8, v80, v81 offset1:66
	s_waitcnt vmcnt(28)
	ds_write2_b32 v8, v82, v83 offset0:132 offset1:198
	s_waitcnt vmcnt(26)
	ds_write2_b32 v9, v84, v85 offset0:8 offset1:74
	s_waitcnt vmcnt(24)
	ds_write2_b32 v9, v86, v87 offset0:140 offset1:206
	s_waitcnt vmcnt(22)
	ds_write2_b32 v10, v88, v89 offset0:16 offset1:82
	s_waitcnt vmcnt(20)
	ds_write2_b32 v10, v90, v91 offset0:148 offset1:214
	s_waitcnt vmcnt(18)
	ds_write2_b32 v11, v92, v93 offset0:24 offset1:90
	s_waitcnt vmcnt(16)
	ds_write2_b32 v11, v94, v26 offset0:156 offset1:222
	s_waitcnt vmcnt(14)
	ds_write2_b32 v12, v27, v28 offset0:32 offset1:98
	s_waitcnt vmcnt(12)
	ds_write2_b32 v12, v29, v30 offset0:164 offset1:230
	s_waitcnt vmcnt(10)
	ds_write2_b32 v13, v31, v40 offset0:40 offset1:106
	s_waitcnt vmcnt(8)
	ds_write2_b32 v13, v41, v42 offset0:172 offset1:238
	s_waitcnt vmcnt(6)
	ds_write2_b32 v14, v43, v44 offset0:48 offset1:114
	s_waitcnt vmcnt(4)
	ds_write2_b32 v14, v45, v95 offset0:180 offset1:246
	s_waitcnt vmcnt(2)
	ds_write2_b32 v15, v96, v97 offset0:56 offset1:122
	s_waitcnt vmcnt(0)
	ds_write2_b32 v15, v46, v47 offset0:188 offset1:254
	v_lshl_add_u64 v[32:33], v[16:17], 0, v[18:19]
	v_lshlrev_b64 v[18:19], 11, v[20:21]
	v_lshlrev_b64 v[20:21], 11, v[22:23]
	v_lshlrev_b64 v[22:23], 11, v[24:25]
	s_waitcnt lgkmcnt(0)
	v_lshl_add_u64 v[36:37], v[16:17], 0, v[20:21]
	v_lshl_add_u64 v[38:39], v[16:17], 0, v[22:23]
	ds_read2_b32 v[20:21], v7 offset0:33 offset1:41
	ds_read2_b32 v[22:23], v7 offset1:8
	ds_read2_b32 v[24:25], v7 offset0:66 offset1:74
	ds_read2_b32 v[26:27], v7 offset0:99 offset1:107
	ds_read2_b32 v[28:29], v7 offset0:132 offset1:140
	ds_read2_b32 v[30:31], v7 offset0:165 offset1:173
	ds_read2_b32 v[40:41], v7 offset0:198 offset1:206
	ds_read2_b32 v[42:43], v7 offset0:231 offset1:239
	ds_read2_b32 v[44:45], v7 offset0:49 offset1:57
	ds_read2_b32 v[46:47], v7 offset0:16 offset1:24
	ds_read2_b32 v[48:49], v7 offset0:82 offset1:90
	ds_read2_b32 v[50:51], v7 offset0:115 offset1:123
	ds_read2_b32 v[52:53], v7 offset0:148 offset1:156
	ds_read2_b32 v[54:55], v7 offset0:181 offset1:189
	ds_read2_b32 v[56:57], v7 offset0:214 offset1:222
	ds_read2_b32 v[58:59], v7 offset0:247 offset1:255
	v_lshl_add_u64 v[34:35], v[16:17], 0, v[18:19]
	s_waitcnt lgkmcnt(14)
	v_cvt_pk_bf16_f32 v16, v22, v20
	s_waitcnt lgkmcnt(12)
	v_cvt_pk_bf16_f32 v17, v24, v26
	s_waitcnt lgkmcnt(10)
	v_cvt_pk_bf16_f32 v18, v28, v30
	s_waitcnt lgkmcnt(8)
	v_cvt_pk_bf16_f32 v19, v40, v42
	v_cvt_pk_bf16_f32 v20, v23, v21
	v_cvt_pk_bf16_f32 v21, v25, v27
	v_cvt_pk_bf16_f32 v22, v29, v31
	v_cvt_pk_bf16_f32 v23, v41, v43
	s_waitcnt lgkmcnt(6)
	v_cvt_pk_bf16_f32 v24, v46, v44
	s_waitcnt lgkmcnt(4)
	v_cvt_pk_bf16_f32 v25, v48, v50
	s_waitcnt lgkmcnt(2)
	v_cvt_pk_bf16_f32 v26, v52, v54
	s_waitcnt lgkmcnt(0)
	v_cvt_pk_bf16_f32 v27, v56, v58
	v_cvt_pk_bf16_f32 v28, v47, v45
	v_cvt_pk_bf16_f32 v29, v49, v51
	v_cvt_pk_bf16_f32 v30, v53, v55
	v_cvt_pk_bf16_f32 v31, v57, v59
	global_store_dwordx4 v[32:33], v[16:19], off nt
	global_store_dwordx4 v[34:35], v[20:23], off nt
	global_store_dwordx4 v[36:37], v[24:27], off nt
	global_store_dwordx4 v[38:39], v[28:31], off nt
	s_waitcnt lgkmcnt(0)
	s_add_i32 s7, s7, s93
	s_add_i32 s3, s3, s6
	s_cmpk_lt_i32 s7, 0x400
	s_cbranch_scc1 .LBB0_48

; template <int MODE> __device__ __forceinline__ void transpose_item(const float* W, int K, int N, bf16_t* WT, LAS float* scr, int item, int lane) {
;     const int nblk = N / 32, kb = item / nblk, nb = item % nblk, k0 = 64 * kb, n0 = 32 * nb;
;     float tv[32];
; #pragma unroll
;     for (int i = 0; i < 32; ++i) tv[i] = W[(size_t)(k0 + 2 * i + (lane >> 5)) * N + n0 + (lane & 31)];
.LBB0_51:
	s_ashr_i32 s8, s7, 31
	s_lshr_b32 s8, s8, 26
	s_add_i32 s9, s7, s8
	s_and_b32 s8, s9, 0xffffffc0
	s_lshl_b32 s9, s9, 5
	s_and_b32 s9, s9, 0xfffff800
	v_add_u32_e32 v16, s8, v5
	s_sub_i32 s10, s3, s9
	v_add_u32_e32 v26, 10, v16
	v_add_u32_e32 v28, 12, v16
	v_add_u32_e32 v30, 14, v16
	v_add_u32_e32 v40, 24, v16
	v_add_u32_e32 v42, 26, v16
	v_add_u32_e32 v44, 28, v16
	v_add_u32_e32 v46, 30, v16
	v_ashrrev_i32_e32 v17, 31, v16
	v_add_u32_e32 v18, 2, v16
	v_add_u32_e32 v20, 4, v16
	v_add_u32_e32 v22, 6, v16
	v_add_u32_e32 v24, 8, v16
	v_add_u32_e32 v32, 16, v16
	v_add_u32_e32 v34, 18, v16
	v_add_u32_e32 v36, 20, v16
	v_add_u32_e32 v38, 22, v16
	v_add_u32_e32 v48, 32, v16
	v_add_u32_e32 v50, 34, v16
	v_add_u32_e32 v52, 36, v16
	v_add_u32_e32 v54, 38, v16
	v_add_u32_e32 v56, 40, v16
	v_add_u32_e32 v58, 42, v16
	v_add_u32_e32 v60, 44, v16
	v_add_u32_e32 v62, 46, v16
	v_add_u32_e32 v64, 48, v16
	v_add_u32_e32 v66, 50, v16
	v_add_u32_e32 v68, 52, v16
	v_add_u32_e32 v70, 54, v16
	v_add_u32_e32 v72, 56, v16
	v_add_u32_e32 v74, 58, v16
	v_add_u32_e32 v76, 60, v16
	v_add_u32_e32 v78, 62, v16
	s_ashr_i32 s11, s10, 31
	v_ashrrev_i32_e32 v27, 31, v26
	v_ashrrev_i32_e32 v29, 31, v28
	v_ashrrev_i32_e32 v31, 31, v30
	v_ashrrev_i32_e32 v41, 31, v40
	v_ashrrev_i32_e32 v43, 31, v42
	v_ashrrev_i32_e32 v45, 31, v44
	v_ashrrev_i32_e32 v47, 31, v46
	v_lshlrev_b64 v[16:17], 13, v[16:17]
	v_ashrrev_i32_e32 v19, 31, v18
	v_ashrrev_i32_e32 v21, 31, v20
	v_ashrrev_i32_e32 v23, 31, v22
	v_ashrrev_i32_e32 v25, 31, v24
	v_ashrrev_i32_e32 v33, 31, v32
	v_ashrrev_i32_e32 v35, 31, v34
	v_ashrrev_i32_e32 v37, 31, v36
	v_ashrrev_i32_e32 v39, 31, v38
	v_ashrrev_i32_e32 v49, 31, v48
	v_ashrrev_i32_e32 v51, 31, v50
	v_ashrrev_i32_e32 v53, 31, v52
	v_ashrrev_i32_e32 v55, 31, v54
	v_ashrrev_i32_e32 v57, 31, v56
	v_ashrrev_i32_e32 v59, 31, v58
	v_ashrrev_i32_e32 v61, 31, v60
	v_ashrrev_i32_e32 v63, 31, v62
	v_ashrrev_i32_e32 v65, 31, v64
	v_ashrrev_i32_e32 v67, 31, v66
	v_ashrrev_i32_e32 v69, 31, v68
	v_ashrrev_i32_e32 v71, 31, v70
	v_ashrrev_i32_e32 v73, 31, v72
	v_ashrrev_i32_e32 v75, 31, v74
	v_ashrrev_i32_e32 v77, 31, v76
	v_ashrrev_i32_e32 v79, 31, v78
	v_lshl_add_u64 v[80:81], s[10:11], 2, v[0:1]
	v_lshlrev_b64 v[26:27], 13, v[26:27]
	v_lshlrev_b64 v[28:29], 13, v[28:29]
	v_lshlrev_b64 v[30:31], 13, v[30:31]
	v_lshlrev_b64 v[40:41], 13, v[40:41]
	v_lshlrev_b64 v[42:43], 13, v[42:43]
	v_lshlrev_b64 v[44:45], 13, v[44:45]
	v_lshlrev_b64 v[46:47], 13, v[46:47]
	v_lshlrev_b64 v[18:19], 13, v[18:19]
	v_lshlrev_b64 v[20:21], 13, v[20:21]
	v_lshlrev_b64 v[22:23], 13, v[22:23]
	v_lshlrev_b64 v[24:25], 13, v[24:25]
	v_lshlrev_b64 v[32:33], 13, v[32:33]
	v_lshlrev_b64 v[34:35], 13, v[34:35]
	v_lshlrev_b64 v[36:37], 13, v[36:37]
	v_lshlrev_b64 v[38:39], 13, v[38:39]
	v_lshlrev_b64 v[48:49], 13, v[48:49]
	v_lshlrev_b64 v[50:51], 13, v[50:51]
	v_lshlrev_b64 v[52:53], 13, v[52:53]
	v_lshlrev_b64 v[54:55], 13, v[54:55]
	v_lshlrev_b64 v[56:57], 13, v[56:57]
	v_lshlrev_b64 v[58:59], 13, v[58:59]
	v_lshlrev_b64 v[60:61], 13, v[60:61]
	v_lshlrev_b64 v[62:63], 13, v[62:63]
	v_lshlrev_b64 v[64:65], 13, v[64:65]
	v_lshlrev_b64 v[66:67], 13, v[66:67]
	v_lshlrev_b64 v[68:69], 13, v[68:69]
	v_lshlrev_b64 v[70:71], 13, v[70:71]
	v_lshlrev_b64 v[72:73], 13, v[72:73]
	v_lshlrev_b64 v[74:75], 13, v[74:75]
	v_lshlrev_b64 v[76:77], 13, v[76:77]
	v_lshlrev_b64 v[78:79], 13, v[78:79]
	v_lshl_add_u64 v[16:17], v[80:81], 0, v[16:17]
	v_lshl_add_u64 v[26:27], v[80:81], 0, v[26:27]
	v_lshl_add_u64 v[28:29], v[80:81], 0, v[28:29]
	v_lshl_add_u64 v[30:31], v[80:81], 0, v[30:31]
	v_lshl_add_u64 v[40:41], v[80:81], 0, v[40:41]
	v_lshl_add_u64 v[42:43], v[80:81], 0, v[42:43]
	v_lshl_add_u64 v[44:45], v[80:81], 0, v[44:45]
	v_lshl_add_u64 v[46:47], v[80:81], 0, v[46:47]
	v_lshl_add_u64 v[18:19], v[80:81], 0, v[18:19]
	v_lshl_add_u64 v[20:21], v[80:81], 0, v[20:21]
	v_lshl_add_u64 v[22:23], v[80:81], 0, v[22:23]
	v_lshl_add_u64 v[24:25], v[80:81], 0, v[24:25]
	v_lshl_add_u64 v[32:33], v[80:81], 0, v[32:33]
	v_lshl_add_u64 v[34:35], v[80:81], 0, v[34:35]
	v_lshl_add_u64 v[36:37], v[80:81], 0, v[36:37]
	v_lshl_add_u64 v[38:39], v[80:81], 0, v[38:39]
	v_lshl_add_u64 v[48:49], v[80:81], 0, v[48:49]
	v_lshl_add_u64 v[50:51], v[80:81], 0, v[50:51]
	v_lshl_add_u64 v[52:53], v[80:81], 0, v[52:53]
	v_lshl_add_u64 v[54:55], v[80:81], 0, v[54:55]
	v_lshl_add_u64 v[56:57], v[80:81], 0, v[56:57]
	v_lshl_add_u64 v[58:59], v[80:81], 0, v[58:59]
	v_lshl_add_u64 v[60:61], v[80:81], 0, v[60:61]
	v_lshl_add_u64 v[62:63], v[80:81], 0, v[62:63]
	v_lshl_add_u64 v[64:65], v[80:81], 0, v[64:65]
	v_lshl_add_u64 v[66:67], v[80:81], 0, v[66:67]
	v_lshl_add_u64 v[68:69], v[80:81], 0, v[68:69]
	v_lshl_add_u64 v[70:71], v[80:81], 0, v[70:71]
	v_lshl_add_u64 v[72:73], v[80:81], 0, v[72:73]
	v_lshl_add_u64 v[74:75], v[80:81], 0, v[74:75]
	v_lshl_add_u64 v[76:77], v[80:81], 0, v[76:77]
	v_lshl_add_u64 v[78:79], v[80:81], 0, v[78:79]
	global_load_dword v80, v[16:17], off nt
	global_load_dword v81, v[18:19], off nt
	global_load_dword v82, v[20:21], off nt
	global_load_dword v83, v[22:23], off nt
	global_load_dword v84, v[24:25], off nt
	global_load_dword v85, v[26:27], off nt
	global_load_dword v86, v[28:29], off nt
	global_load_dword v87, v[30:31], off nt
	global_load_dword v88, v[32:33], off nt
	global_load_dword v89, v[34:35], off nt
	global_load_dword v90, v[36:37], off nt
	global_load_dword v91, v[38:39], off nt
	global_load_dword v92, v[40:41], off nt
	global_load_dword v93, v[42:43], off nt
	global_load_dword v94, v[44:45], off nt
	global_load_dword v26, v[46:47], off nt
	global_load_dword v27, v[48:49], off nt
	global_load_dword v28, v[50:51], off nt
	global_load_dword v29, v[52:53], off nt
	global_load_dword v30, v[54:55], off nt
	global_load_dword v31, v[56:57], off nt
	global_load_dword v40, v[58:59], off nt
	global_load_dword v41, v[60:61], off nt
	global_load_dword v42, v[62:63], off nt
	global_load_dword v43, v[64:65], off nt
	global_load_dword v44, v[66:67], off nt
	global_load_dword v45, v[68:69], off nt
	global_load_dword v95, v[70:71], off nt
	global_load_dword v96, v[72:73], off nt
	global_load_dword v97, v[74:75], off nt
	global_load_dword v46, v[76:77], off nt
	global_load_dword v47, v[78:79], off nt
	v_add_u32_e32 v18, s10, v6
	s_ashr_i32 s9, s8, 31
	v_ashrrev_i32_e32 v19, 31, v18
	v_add_u32_e32 v20, 8, v18
	v_add_u32_e32 v22, 16, v18
	v_add_u32_e32 v24, 24, v18
	v_lshl_add_u64 v[16:17], s[8:9], 1, v[2:3]
	v_lshlrev_b64 v[18:19], 11, v[18:19]
	v_ashrrev_i32_e32 v21, 31, v20
	v_ashrrev_i32_e32 v23, 31, v22
	v_ashrrev_i32_e32 v25, 31, v24
	s_waitcnt vmcnt(30)
; __device__ __forceinline__ unsigned cvt_pk_bf16(float lo, float hi) { const f32x2c v = {lo, hi}; const bf16x2c b = __builtin_convertvector(v, bf16x2c); return __builtin_bit_cast(unsigned, b); }
; #define LAS __attribute__((address_space(3)))
; template <int MODE> __device__ __forceinline__ void transpose_item(const float* W, int K, int N, bf16_t* WT, LAS float* scr, int item, int lane) {
;     ...
;     for (int i = 0; i < 32; ++i) scr[(2 * i + (lane >> 5)) * 33 + (lane & 31)] = tv[i];
;     asm volatile("s_waitcnt lgkmcnt(0)" ::: "memory");
;     const int c = lane & 7, dr0 = dest_row<MODE>(n0);
; #pragma unroll
;     for (int j = 0; j < 4; ++j) { const int n = (lane >> 3) + 8 * j; const LAS float* s = scr + (8 * c) * 33 + n;
;         u32x4 o; o.x = cvt_pk_bf16(s[0 * 33], s[1 * 33]); o.y = cvt_pk_bf16(s[2 * 33], s[3 * 33]); o.z = cvt_pk_bf16(s[4 * 33], s[5 * 33]); o.w = cvt_pk_bf16(s[6 * 33], s[7 * 33]);
;         *(u32x4*)(WT + (size_t)(dr0 + n) * K + k0 + 8 * c) = o; }
;     asm volatile("s_waitcnt lgkmcnt(0)" ::: "memory");
	ds_write2_b32 v8, v80, v81 offset1:66
	s_waitcnt vmcnt(28)
	ds_write2_b32 v8, v82, v83 offset0:132 offset1:198
	s_waitcnt vmcnt(26)
	ds_write2_b32 v9, v84, v85 offset0:8 offset1:74
	s_waitcnt vmcnt(24)
	ds_write2_b32 v9, v86, v87 offset0:140 offset1:206
	s_waitcnt vmcnt(22)
	ds_write2_b32 v10, v88, v89 offset0:16 offset1:82
	s_waitcnt vmcnt(20)
	ds_write2_b32 v10, v90, v91 offset0:148 offset1:214
	s_waitcnt vmcnt(18)
	ds_write2_b32 v11, v92, v93 offset0:24 offset1:90
	s_waitcnt vmcnt(16)
	ds_write2_b32 v11, v94, v26 offset0:156 offset1:222
	s_waitcnt vmcnt(14)
	ds_write2_b32 v12, v27, v28 offset0:32 offset1:98
	s_waitcnt vmcnt(12)
	ds_write2_b32 v12, v29, v30 offset0:164 offset1:230
	s_waitcnt vmcnt(10)
	ds_write2_b32 v13, v31, v40 offset0:40 offset1:106
	s_waitcnt vmcnt(8)
	ds_write2_b32 v13, v41, v42 offset0:172 offset1:238
	s_waitcnt vmcnt(6)
	ds_write2_b32 v14, v43, v44 offset0:48 offset1:114
	s_waitcnt vmcnt(4)
	ds_write2_b32 v14, v45, v95 offset0:180 offset1:246
	s_waitcnt vmcnt(2)
	ds_write2_b32 v15, v96, v97 offset0:56 offset1:122
	s_waitcnt vmcnt(0)
	ds_write2_b32 v15, v46, v47 offset0:188 offset1:254
	v_lshl_add_u64 v[32:33], v[16:17], 0, v[18:19]
	v_lshlrev_b64 v[18:19], 11, v[20:21]
	v_lshlrev_b64 v[20:21], 11, v[22:23]
	v_lshlrev_b64 v[22:23], 11, v[24:25]
	s_waitcnt lgkmcnt(0)
	v_lshl_add_u64 v[36:37], v[16:17], 0, v[20:21]
	v_lshl_add_u64 v[38:39], v[16:17], 0, v[22:23]
	ds_read2_b32 v[20:21], v7 offset0:33 offset1:41
	ds_read2_b32 v[22:23], v7 offset1:8
	ds_read2_b32 v[24:25], v7 offset0:66 offset1:74
	ds_read2_b32 v[26:27], v7 offset0:99 offset1:107
	ds_read2_b32 v[28:29], v7 offset0:132 offset1:140
	ds_read2_b32 v[30:31], v7 offset0:165 offset1:173
	ds_read2_b32 v[40:41], v7 offset0:198 offset1:206
	ds_read2_b32 v[42:43], v7 offset0:231 offset1:239
	ds_read2_b32 v[44:45], v7 offset0:49 offset1:57
	ds_read2_b32 v[46:47], v7 offset0:16 offset1:24
	ds_read2_b32 v[48:49], v7 offset0:82 offset1:90
	ds_read2_b32 v[50:51], v7 offset0:115 offset1:123
	ds_read2_b32 v[52:53], v7 offset0:148 offset1:156
	ds_read2_b32 v[54:55], v7 offset0:181 offset1:189
	ds_read2_b32 v[56:57], v7 offset0:214 offset1:222
	ds_read2_b32 v[58:59], v7 offset0:247 offset1:255
	v_lshl_add_u64 v[34:35], v[16:17], 0, v[18:19]
	s_waitcnt lgkmcnt(14)
	v_cvt_pk_bf16_f32 v16, v22, v20
	s_waitcnt lgkmcnt(12)
	v_cvt_pk_bf16_f32 v17, v24, v26
	s_waitcnt lgkmcnt(10)
	v_cvt_pk_bf16_f32 v18, v28, v30
	s_waitcnt lgkmcnt(8)
	v_cvt_pk_bf16_f32 v19, v40, v42
	v_cvt_pk_bf16_f32 v20, v23, v21
	v_cvt_pk_bf16_f32 v21, v25, v27
	v_cvt_pk_bf16_f32 v22, v29, v31
	v_cvt_pk_bf16_f32 v23, v41, v43
	s_waitcnt lgkmcnt(6)
	v_cvt_pk_bf16_f32 v24, v46, v44
	s_waitcnt lgkmcnt(4)
	v_cvt_pk_bf16_f32 v25, v48, v50
	s_waitcnt lgkmcnt(2)
	v_cvt_pk_bf16_f32 v26, v52, v54
	s_waitcnt lgkmcnt(0)
	v_cvt_pk_bf16_f32 v27, v56, v58
	v_cvt_pk_bf16_f32 v28, v47, v45
	v_cvt_pk_bf16_f32 v29, v49, v51
	v_cvt_pk_bf16_f32 v30, v53, v55
	v_cvt_pk_bf16_f32 v31, v57, v59
	global_store_dwordx4 v[32:33], v[16:19], off nt
	global_store_dwordx4 v[34:35], v[20:23], off nt
	global_store_dwordx4 v[36:37], v[24:27], off nt
	global_store_dwordx4 v[38:39], v[28:31], off nt
	s_waitcnt lgkmcnt(0)
	s_add_i32 s7, s7, s93
	s_add_i32 s3, s3, s6
	s_cmpk_lt_i32 s7, 0x400
	s_cbranch_scc1 .LBB0_51

; __device__ __forceinline__ unsigned cvt_pk_bf16(float lo, float hi) { const f32x2c v = {lo, hi}; const bf16x2c b = __builtin_convertvector(v, bf16x2c); return __builtin_bit_cast(unsigned, b); }
; #define LAS __attribute__((address_space(3)))
; template <int MODE> __device__ __forceinline__ void transpose_item(const float* W, int K, int N, bf16_t* WT, LAS float* scr, int item, int lane) {
;     const int nblk = N / 32, kb = item / nblk, nb = item % nblk, k0 = 64 * kb, n0 = 32 * nb;
;     float tv[32];
; #pragma unroll
;     for (int i = 0; i < 32; ++i) tv[i] = W[(size_t)(k0 + 2 * i + (lane >> 5)) * N + n0 + (lane & 31)];
; #pragma unroll
;     for (int i = 0; i < 32; ++i) scr[(2 * i + (lane >> 5)) * 33 + (lane & 31)] = tv[i];
;     asm volatile("s_waitcnt lgkmcnt(0)" ::: "memory");
;     const int c = lane & 7, dr0 = dest_row<MODE>(n0);
; #pragma unroll
;     for (int j = 0; j < 4; ++j) { const int n = (lane >> 3) + 8 * j; const LAS float* s = scr + (8 * c) * 33 + n;
;         u32x4 o; o.x = cvt_pk_bf16(s[0 * 33], s[1 * 33]); o.y = cvt_pk_bf16(s[2 * 33], s[3 * 33]); o.z = cvt_pk_bf16(s[4 * 33], s[5 * 33]); o.w = cvt_pk_bf16(s[6 * 33], s[7 * 33]);
;         *(u32x4*)(WT + (size_t)(dr0 + n) * K + k0 + 8 * c) = o; }
;     asm volatile("s_waitcnt lgkmcnt(0)" ::: "memory");
; }
.LBB0_54:
	s_ashr_i32 s8, s7, 31
	s_lshr_b32 s8, s8, 26
	s_add_i32 s9, s7, s8
	s_and_b32 s8, s9, 0xffffffc0
	s_lshl_b32 s9, s9, 5
	s_and_b32 s9, s9, 0xfffff800
	v_add_u32_e32 v16, s8, v5
	s_sub_i32 s10, s3, s9
	v_add_u32_e32 v26, 10, v16
	v_add_u32_e32 v28, 12, v16
	v_add_u32_e32 v30, 14, v16
	v_add_u32_e32 v40, 24, v16
	v_add_u32_e32 v42, 26, v16
	v_add_u32_e32 v44, 28, v16
	v_add_u32_e32 v46, 30, v16
	v_ashrrev_i32_e32 v17, 31, v16
	v_add_u32_e32 v18, 2, v16
	v_add_u32_e32 v20, 4, v16
	v_add_u32_e32 v22, 6, v16
	v_add_u32_e32 v24, 8, v16
	v_add_u32_e32 v32, 16, v16
	v_add_u32_e32 v34, 18, v16
	v_add_u32_e32 v36, 20, v16
	v_add_u32_e32 v38, 22, v16
	v_add_u32_e32 v48, 32, v16
	v_add_u32_e32 v50, 34, v16
	v_add_u32_e32 v52, 36, v16
	v_add_u32_e32 v54, 38, v16
	v_add_u32_e32 v56, 40, v16
	v_add_u32_e32 v58, 42, v16
	v_add_u32_e32 v60, 44, v16
	v_add_u32_e32 v62, 46, v16
	v_add_u32_e32 v64, 48, v16
	v_add_u32_e32 v66, 50, v16
	v_add_u32_e32 v68, 52, v16
	v_add_u32_e32 v70, 54, v16
	v_add_u32_e32 v72, 56, v16
	v_add_u32_e32 v74, 58, v16
	v_add_u32_e32 v76, 60, v16
	v_add_u32_e32 v78, 62, v16
	s_ashr_i32 s11, s10, 31
	v_ashrrev_i32_e32 v27, 31, v26
	v_ashrrev_i32_e32 v29, 31, v28
	v_ashrrev_i32_e32 v31, 31, v30
	v_ashrrev_i32_e32 v41, 31, v40
	v_ashrrev_i32_e32 v43, 31, v42
	v_ashrrev_i32_e32 v45, 31, v44
	v_ashrrev_i32_e32 v47, 31, v46
	v_lshlrev_b64 v[16:17], 13, v[16:17]
	v_ashrrev_i32_e32 v19, 31, v18
	v_ashrrev_i32_e32 v21, 31, v20
	v_ashrrev_i32_e32 v23, 31, v22
	v_ashrrev_i32_e32 v25, 31, v24
	v_ashrrev_i32_e32 v33, 31, v32
	v_ashrrev_i32_e32 v35, 31, v34
	v_ashrrev_i32_e32 v37, 31, v36
	v_ashrrev_i32_e32 v39, 31, v38
	v_ashrrev_i32_e32 v49, 31, v48
	v_ashrrev_i32_e32 v51, 31, v50
	v_ashrrev_i32_e32 v53, 31, v52
	v_ashrrev_i32_e32 v55, 31, v54
	v_ashrrev_i32_e32 v57, 31, v56
	v_ashrrev_i32_e32 v59, 31, v58
	v_ashrrev_i32_e32 v61, 31, v60
	v_ashrrev_i32_e32 v63, 31, v62
	v_ashrrev_i32_e32 v65, 31, v64
	v_ashrrev_i32_e32 v67, 31, v66
	v_ashrrev_i32_e32 v69, 31, v68
	v_ashrrev_i32_e32 v71, 31, v70
	v_ashrrev_i32_e32 v73, 31, v72
	v_ashrrev_i32_e32 v75, 31, v74
	v_ashrrev_i32_e32 v77, 31, v76
	v_ashrrev_i32_e32 v79, 31, v78
	v_lshl_add_u64 v[80:81], s[10:11], 2, v[0:1]
	v_lshlrev_b64 v[26:27], 13, v[26:27]
	v_lshlrev_b64 v[28:29], 13, v[28:29]
	v_lshlrev_b64 v[30:31], 13, v[30:31]
	v_lshlrev_b64 v[40:41], 13, v[40:41]
	v_lshlrev_b64 v[42:43], 13, v[42:43]
	v_lshlrev_b64 v[44:45], 13, v[44:45]
	v_lshlrev_b64 v[46:47], 13, v[46:47]
	v_lshlrev_b64 v[18:19], 13, v[18:19]
	v_lshlrev_b64 v[20:21], 13, v[20:21]
	v_lshlrev_b64 v[22:23], 13, v[22:23]
	v_lshlrev_b64 v[24:25], 13, v[24:25]
	v_lshlrev_b64 v[32:33], 13, v[32:33]
	v_lshlrev_b64 v[34:35], 13, v[34:35]
	v_lshlrev_b64 v[36:37], 13, v[36:37]
	v_lshlrev_b64 v[38:39], 13, v[38:39]
	v_lshlrev_b64 v[48:49], 13, v[48:49]
	v_lshlrev_b64 v[50:51], 13, v[50:51]
	v_lshlrev_b64 v[52:53], 13, v[52:53]
	v_lshlrev_b64 v[54:55], 13, v[54:55]
	v_lshlrev_b64 v[56:57], 13, v[56:57]
	v_lshlrev_b64 v[58:59], 13, v[58:59]
	v_lshlrev_b64 v[60:61], 13, v[60:61]
	v_lshlrev_b64 v[62:63], 13, v[62:63]
	v_lshlrev_b64 v[64:65], 13, v[64:65]
	v_lshlrev_b64 v[66:67], 13, v[66:67]
	v_lshlrev_b64 v[68:69], 13, v[68:69]
	v_lshlrev_b64 v[70:71], 13, v[70:71]
	v_lshlrev_b64 v[72:73], 13, v[72:73]
	v_lshlrev_b64 v[74:75], 13, v[74:75]
	v_lshlrev_b64 v[76:77], 13, v[76:77]
	v_lshlrev_b64 v[78:79], 13, v[78:79]
	v_lshl_add_u64 v[16:17], v[80:81], 0, v[16:17]
	v_lshl_add_u64 v[26:27], v[80:81], 0, v[26:27]
	v_lshl_add_u64 v[28:29], v[80:81], 0, v[28:29]
	v_lshl_add_u64 v[30:31], v[80:81], 0, v[30:31]
	v_lshl_add_u64 v[40:41], v[80:81], 0, v[40:41]
	v_lshl_add_u64 v[42:43], v[80:81], 0, v[42:43]
	v_lshl_add_u64 v[44:45], v[80:81], 0, v[44:45]
	v_lshl_add_u64 v[46:47], v[80:81], 0, v[46:47]
	v_lshl_add_u64 v[18:19], v[80:81], 0, v[18:19]
	v_lshl_add_u64 v[20:21], v[80:81], 0, v[20:21]
	v_lshl_add_u64 v[22:23], v[80:81], 0, v[22:23]
	v_lshl_add_u64 v[24:25], v[80:81], 0, v[24:25]
	v_lshl_add_u64 v[32:33], v[80:81], 0, v[32:33]
	v_lshl_add_u64 v[34:35], v[80:81], 0, v[34:35]
	v_lshl_add_u64 v[36:37], v[80:81], 0, v[36:37]
	v_lshl_add_u64 v[38:39], v[80:81], 0, v[38:39]
	v_lshl_add_u64 v[48:49], v[80:81], 0, v[48:49]
	v_lshl_add_u64 v[50:51], v[80:81], 0, v[50:51]
	v_lshl_add_u64 v[52:53], v[80:81], 0, v[52:53]
	v_lshl_add_u64 v[54:55], v[80:81], 0, v[54:55]
	v_lshl_add_u64 v[56:57], v[80:81], 0, v[56:57]
	v_lshl_add_u64 v[58:59], v[80:81], 0, v[58:59]
	v_lshl_add_u64 v[60:61], v[80:81], 0, v[60:61]
	v_lshl_add_u64 v[62:63], v[80:81], 0, v[62:63]
	v_lshl_add_u64 v[64:65], v[80:81], 0, v[64:65]
	v_lshl_add_u64 v[66:67], v[80:81], 0, v[66:67]
	v_lshl_add_u64 v[68:69], v[80:81], 0, v[68:69]
	v_lshl_add_u64 v[70:71], v[80:81], 0, v[70:71]
	v_lshl_add_u64 v[72:73], v[80:81], 0, v[72:73]
	v_lshl_add_u64 v[74:75], v[80:81], 0, v[74:75]
	v_lshl_add_u64 v[76:77], v[80:81], 0, v[76:77]
	v_lshl_add_u64 v[78:79], v[80:81], 0, v[78:79]
	global_load_dword v80, v[16:17], off nt
	global_load_dword v81, v[18:19], off nt
	global_load_dword v82, v[20:21], off nt
	global_load_dword v83, v[22:23], off nt
	global_load_dword v84, v[24:25], off nt
	global_load_dword v85, v[26:27], off nt
	global_load_dword v86, v[28:29], off nt
	global_load_dword v87, v[30:31], off nt
	global_load_dword v88, v[32:33], off nt
	global_load_dword v89, v[34:35], off nt
	global_load_dword v90, v[36:37], off nt
	global_load_dword v91, v[38:39], off nt
	global_load_dword v92, v[40:41], off nt
	global_load_dword v93, v[42:43], off nt
	global_load_dword v94, v[44:45], off nt
	global_load_dword v26, v[46:47], off nt
	global_load_dword v27, v[48:49], off nt
	global_load_dword v28, v[50:51], off nt
	global_load_dword v29, v[52:53], off nt
	global_load_dword v30, v[54:55], off nt
	global_load_dword v31, v[56:57], off nt
	global_load_dword v40, v[58:59], off nt
	global_load_dword v41, v[60:61], off nt
	global_load_dword v42, v[62:63], off nt
	global_load_dword v43, v[64:65], off nt
	global_load_dword v44, v[66:67], off nt
	global_load_dword v45, v[68:69], off nt
	global_load_dword v95, v[70:71], off nt
	global_load_dword v96, v[72:73], off nt
	global_load_dword v97, v[74:75], off nt
	global_load_dword v46, v[76:77], off nt
	global_load_dword v47, v[78:79], off nt
	v_add_u32_e32 v18, s10, v6
	s_ashr_i32 s9, s8, 31
	v_ashrrev_i32_e32 v19, 31, v18
	v_add_u32_e32 v20, 8, v18
	v_add_u32_e32 v22, 16, v18
	v_add_u32_e32 v24, 24, v18
	v_lshl_add_u64 v[16:17], s[8:9], 1, v[2:3]
	v_lshlrev_b64 v[18:19], 12, v[18:19]
	v_ashrrev_i32_e32 v21, 31, v20
	v_ashrrev_i32_e32 v23, 31, v22
	v_ashrrev_i32_e32 v25, 31, v24
	s_waitcnt vmcnt(30)
; __device__ __forceinline__ unsigned cvt_pk_bf16(float lo, float hi) { const f32x2c v = {lo, hi}; const bf16x2c b = __builtin_convertvector(v, bf16x2c); return __builtin_bit_cast(unsigned, b); }
; #define LAS __attribute__((address_space(3)))
; template <int MODE> __device__ __forceinline__ void transpose_item(const float* W, int K, int N, bf16_t* WT, LAS float* scr, int item, int lane) {
;     ...
;     for (int i = 0; i < 32; ++i) scr[(2 * i + (lane >> 5)) * 33 + (lane & 31)] = tv[i];
;     asm volatile("s_waitcnt lgkmcnt(0)" ::: "memory");
;     const int c = lane & 7, dr0 = dest_row<MODE>(n0);
; #pragma unroll
;     for (int j = 0; j < 4; ++j) { const int n = (lane >> 3) + 8 * j; const LAS float* s = scr + (8 * c) * 33 + n;
;         u32x4 o; o.x = cvt_pk_bf16(s[0 * 33], s[1 * 33]); o.y = cvt_pk_bf16(s[2 * 33], s[3 * 33]); o.z = cvt_pk_bf16(s[4 * 33], s[5 * 33]); o.w = cvt_pk_bf16(s[6 * 33], s[7 * 33]);
;         *(u32x4*)(WT + (size_t)(dr0 + n) * K + k0 + 8 * c) = o; }
;     asm volatile("s_waitcnt lgkmcnt(0)" ::: "memory");
; }
	ds_write2_b32 v8, v80, v81 offset1:66
	s_waitcnt vmcnt(28)
	ds_write2_b32 v8, v82, v83 offset0:132 offset1:198
	s_waitcnt vmcnt(26)
	ds_write2_b32 v9, v84, v85 offset0:8 offset1:74
	s_waitcnt vmcnt(24)
	ds_write2_b32 v9, v86, v87 offset0:140 offset1:206
	s_waitcnt vmcnt(22)
	ds_write2_b32 v10, v88, v89 offset0:16 offset1:82
	s_waitcnt vmcnt(20)
	ds_write2_b32 v10, v90, v91 offset0:148 offset1:214
	s_waitcnt vmcnt(18)
	ds_write2_b32 v11, v92, v93 offset0:24 offset1:90
	s_waitcnt vmcnt(16)
	ds_write2_b32 v11, v94, v26 offset0:156 offset1:222
	s_waitcnt vmcnt(14)
	ds_write2_b32 v12, v27, v28 offset0:32 offset1:98
	s_waitcnt vmcnt(12)
	ds_write2_b32 v12, v29, v30 offset0:164 offset1:230
	s_waitcnt vmcnt(10)
	ds_write2_b32 v13, v31, v40 offset0:40 offset1:106
	s_waitcnt vmcnt(8)
	ds_write2_b32 v13, v41, v42 offset0:172 offset1:238
	s_waitcnt vmcnt(6)
	ds_write2_b32 v14, v43, v44 offset0:48 offset1:114
	s_waitcnt vmcnt(4)
	ds_write2_b32 v14, v45, v95 offset0:180 offset1:246
	s_waitcnt vmcnt(2)
	ds_write2_b32 v15, v96, v97 offset0:56 offset1:122
	s_waitcnt vmcnt(0)
	ds_write2_b32 v15, v46, v47 offset0:188 offset1:254
	v_lshl_add_u64 v[32:33], v[16:17], 0, v[18:19]
	v_lshlrev_b64 v[18:19], 12, v[20:21]
	v_lshlrev_b64 v[20:21], 12, v[22:23]
	v_lshlrev_b64 v[22:23], 12, v[24:25]
	s_waitcnt lgkmcnt(0)
	v_lshl_add_u64 v[36:37], v[16:17], 0, v[20:21]
	v_lshl_add_u64 v[38:39], v[16:17], 0, v[22:23]
	ds_read2_b32 v[20:21], v7 offset0:33 offset1:41
	ds_read2_b32 v[22:23], v7 offset1:8
	ds_read2_b32 v[24:25], v7 offset0:66 offset1:74
	ds_read2_b32 v[26:27], v7 offset0:99 offset1:107
	ds_read2_b32 v[28:29], v7 offset0:132 offset1:140
	ds_read2_b32 v[30:31], v7 offset0:165 offset1:173
	ds_read2_b32 v[40:41], v7 offset0:198 offset1:206
	ds_read2_b32 v[42:43], v7 offset0:231 offset1:239
	ds_read2_b32 v[44:45], v7 offset0:49 offset1:57
	ds_read2_b32 v[46:47], v7 offset0:16 offset1:24
	ds_read2_b32 v[48:49], v7 offset0:82 offset1:90
	ds_read2_b32 v[50:51], v7 offset0:115 offset1:123
	ds_read2_b32 v[52:53], v7 offset0:148 offset1:156
	ds_read2_b32 v[54:55], v7 offset0:181 offset1:189
	ds_read2_b32 v[56:57], v7 offset0:214 offset1:222
	ds_read2_b32 v[58:59], v7 offset0:247 offset1:255
	v_lshl_add_u64 v[34:35], v[16:17], 0, v[18:19]
	s_waitcnt lgkmcnt(14)
	v_cvt_pk_bf16_f32 v16, v22, v20
	s_waitcnt lgkmcnt(12)
	v_cvt_pk_bf16_f32 v17, v24, v26
	s_waitcnt lgkmcnt(10)
	v_cvt_pk_bf16_f32 v18, v28, v30
	s_waitcnt lgkmcnt(8)
	v_cvt_pk_bf16_f32 v19, v40, v42
	v_cvt_pk_bf16_f32 v20, v23, v21
	v_cvt_pk_bf16_f32 v21, v25, v27
	v_cvt_pk_bf16_f32 v22, v29, v31
	v_cvt_pk_bf16_f32 v23, v41, v43
	s_waitcnt lgkmcnt(6)
	v_cvt_pk_bf16_f32 v24, v46, v44
	s_waitcnt lgkmcnt(4)
	v_cvt_pk_bf16_f32 v25, v48, v50
	s_waitcnt lgkmcnt(2)
	v_cvt_pk_bf16_f32 v26, v52, v54
	s_waitcnt lgkmcnt(0)
	v_cvt_pk_bf16_f32 v27, v56, v58
	v_cvt_pk_bf16_f32 v28, v47, v45
	v_cvt_pk_bf16_f32 v29, v49, v51
	v_cvt_pk_bf16_f32 v30, v53, v55
	v_cvt_pk_bf16_f32 v31, v57, v59
	global_store_dwordx4 v[32:33], v[16:19], off nt
	global_store_dwordx4 v[34:35], v[20:23], off nt
	global_store_dwordx4 v[36:37], v[24:27], off nt
	global_store_dwordx4 v[38:39], v[28:31], off nt
	s_waitcnt lgkmcnt(0)
	s_add_i32 s7, s7, s93
	s_add_i32 s3, s3, s6
	s_cmpk_lt_i32 s7, 0x800
	s_cbranch_scc1 .LBB0_54
